# SWA attention epilogues (latent+context): 8 dwordx2 row-per-lane stores widened to 4 dwordx4 via v_permlane32_swap pairs
# baseline (speedup 1.0000x reference)
.LBB0_649:
	s_load_dwordx4 s[24:27], s[48:49], 0x140
	s_load_dwordx2 s[6:7], s[48:49], 0x130
	ds_bpermute_b32 v34, v112, v107
	s_mov_b32 s9, 0x3fb8aa3b
	s_mov_b64 s[16:17], -1
	s_waitcnt lgkmcnt(0)
	s_add_u32 s0, s26, 0xad00000
	s_addc_u32 s1, s27, 0
	s_ashr_i32 s19, s18, 31
	s_lshl_b64 s[10:11], s[18:19], 2
	s_add_u32 s10, s6, s10
	s_addc_u32 s11, s7, s11
	global_load_dword v35, v1, s[10:11]
	v_add_f32_e32 v34, v107, v34
	s_waitcnt vmcnt(0)
	v_fma_f32 v35, v35, s9, -v106
	v_exp_f32_e32 v35, v35
	v_readlane_b32 s9, v252, 19
	v_add_f32_e32 v34, v34, v35
	v_div_scale_f32 v35, s[10:11], v34, v34, 1.0
	v_rcp_f32_e32 v36, v35
	s_nop 0
	v_fma_f32 v37, -v35, v36, 1.0
	v_fmac_f32_e32 v36, v37, v36
	v_div_scale_f32 v37, vcc, 1.0, v34, 1.0
	v_mul_f32_e32 v38, v37, v36
	v_fma_f32 v39, -v35, v38, v37
	v_fmac_f32_e32 v38, v39, v36
	v_fma_f32 v35, -v35, v38, v37
	v_div_fmas_f32 v35, v35, v36, v38
	v_add_u32_e32 v36, s4, v101
	v_ashrrev_i32_e32 v37, 31, v36
	v_lshlrev_b64 v[36:37], 11, v[36:37]
	v_div_fixup_f32 v34, v35, v34, 1.0
	v_lshl_add_u64 v[36:37], s[0:1], 0, v[36:37]
	v_lshl_add_u64 v[36:37], s[14:15], 1, v[36:37]
	v_pk_mul_f32 v[2:3], v[2:3], v[34:35] op_sel_hi:[1,0]
	v_pk_mul_f32 v[4:5], v[4:5], v[34:35] op_sel_hi:[1,0]
	v_ashrrev_i32_e32 v101, 31, v100
	v_cvt_pk_bf16_f32 v2, v2, v3
	v_cvt_pk_bf16_f32 v3, v4, v5
	v_lshl_add_u64 v[36:37], v[100:101], 2, v[36:37]
	v_pk_mul_f32 v[6:7], v[6:7], v[34:35] op_sel_hi:[1,0]
	v_pk_mul_f32 v[8:9], v[8:9], v[34:35] op_sel_hi:[1,0]
	v_cvt_pk_bf16_f32 v4, v6, v7
	v_cvt_pk_bf16_f32 v5, v8, v9
	s_nop 1
	v_permlane32_swap_b32_e32 v2, v4
	v_permlane32_swap_b32_e32 v3, v5
	global_store_dwordx4 v[36:37], v[2:5], off
	v_pk_mul_f32 v[10:11], v[10:11], v[34:35] op_sel_hi:[1,0]
	v_pk_mul_f32 v[12:13], v[12:13], v[34:35] op_sel_hi:[1,0]
	v_cvt_pk_bf16_f32 v6, v10, v11
	v_cvt_pk_bf16_f32 v7, v12, v13
	s_lshl_b32 s4, s53, 5
	v_pk_mul_f32 v[14:15], v[14:15], v[34:35] op_sel_hi:[1,0]
	v_pk_mul_f32 v[16:17], v[16:17], v[34:35] op_sel_hi:[1,0]
	s_add_i32 s4, s4, s9
	v_cvt_pk_bf16_f32 v8, v14, v15
	v_cvt_pk_bf16_f32 v9, v16, v17
	s_mul_i32 s10, s4, 0xc00
	s_nop 1
	v_permlane32_swap_b32_e32 v6, v8
	v_permlane32_swap_b32_e32 v7, v9
	global_store_dwordx4 v[36:37], v[6:9], off offset:32
	v_pk_mul_f32 v[18:19], v[18:19], v[34:35] op_sel_hi:[1,0]
	v_pk_mul_f32 v[20:21], v[20:21], v[34:35] op_sel_hi:[1,0]
	s_mul_hi_i32 s9, s4, 0xc00
	s_add_u32 s5, s5, s10
	v_cvt_pk_bf16_f32 v10, v18, v19
	v_cvt_pk_bf16_f32 v11, v20, v21
	s_addc_u32 s8, s8, s9
	v_readlane_b32 s10, v254, 8
	v_pk_mul_f32 v[22:23], v[22:23], v[34:35] op_sel_hi:[1,0]
	v_pk_mul_f32 v[24:25], v[24:25], v[34:35] op_sel_hi:[1,0]
	v_readlane_b32 s11, v254, 9
	s_add_u32 s9, s12, s10
	v_cvt_pk_bf16_f32 v12, v22, v23
	v_cvt_pk_bf16_f32 v13, v24, v25
	s_addc_u32 s11, s13, s11
	v_readlane_b32 s10, v254, 4
	s_nop 1
	v_permlane32_swap_b32_e32 v10, v12
	v_permlane32_swap_b32_e32 v11, v13
	global_store_dwordx4 v[36:37], v[10:13], off offset:64
	v_pk_mul_f32 v[26:27], v[26:27], v[34:35] op_sel_hi:[1,0]
	v_pk_mul_f32 v[28:29], v[28:29], v[34:35] op_sel_hi:[1,0]
	s_add_u32 s10, s9, s10
	v_cvt_pk_bf16_f32 v14, v26, v27
	v_cvt_pk_bf16_f32 v15, v28, v29
	s_addc_u32 s11, s11, 0
	v_readlane_b32 s14, v252, 20
	v_pk_mul_f32 v[30:31], v[30:31], v[34:35] op_sel_hi:[1,0]
	v_pk_mul_f32 v[32:33], v[32:33], v[34:35] op_sel_hi:[1,0]
	v_readlane_b32 s15, v252, 21
	s_add_u32 s12, s26, s14
	v_cvt_pk_bf16_f32 v16, v30, v31
	v_cvt_pk_bf16_f32 v17, v32, v33
	s_addc_u32 s13, s27, s15
	s_nop 1
	v_permlane32_swap_b32_e32 v14, v16
	v_permlane32_swap_b32_e32 v15, v17
	global_store_dwordx4 v[36:37], v[14:17], off offset:96
	v_lshl_add_u64 v[100:101], s[10:11], 0, v[0:1]
	v_lshl_add_u64 v[2:3], s[12:13], 0, v[0:1]
	s_mov_b64 s[10:11], 0xc507000
	v_lshl_add_u64 v[102:103], v[2:3], 0, s[10:11]
	s_mov_b64 s[10:11], 0xc507400
	s_add_u32 s14, s26, s14
	v_lshl_add_u64 v[104:105], v[2:3], 0, s[10:11]
	s_mov_b64 s[10:11], 0xc507800
	s_addc_u32 s15, s27, s15
	v_readlane_b32 s9, v254, 7
	v_lshl_add_u64 v[106:107], v[2:3], 0, s[10:11]
	s_mov_b64 s[10:11], 0xc507c00
	s_add_u32 s18, s26, s9
	v_readlane_b32 s9, v254, 10
	v_lshl_add_u64 v[108:109], v[2:3], 0, s[10:11]
	s_addc_u32 s19, s27, s9
	s_mov_b32 s10, 0
	s_branch .LBB0_651
.LBB0_650:
	v_sub_f32_e32 v0, v34, v115
	v_exp_f32_e32 v0, v0
	v_sub_f32_e32 v35, v35, v115
	v_exp_f32_e32 v35, v35
	v_sub_f32_e32 v36, v36, v115
	v_exp_f32_e32 v36, v36
	v_sub_f32_e32 v37, v37, v115
	v_exp_f32_e32 v37, v37
	v_sub_f32_e32 v38, v38, v115
	v_add_f32_e32 v34, 0, v0
	v_exp_f32_e32 v38, v38
	v_sub_f32_e32 v39, v39, v115
	v_add_f32_e32 v34, v35, v34
	v_exp_f32_e32 v39, v39
	v_sub_f32_e32 v40, v40, v115
	v_add_f32_e32 v34, v36, v34
	v_exp_f32_e32 v40, v40
	v_sub_f32_e32 v41, v41, v115
	v_add_f32_e32 v34, v37, v34
	v_exp_f32_e32 v41, v41
	v_sub_f32_e32 v42, v42, v115
	v_add_f32_e32 v34, v38, v34
	v_exp_f32_e32 v42, v42
	v_sub_f32_e32 v43, v43, v115
	v_add_f32_e32 v34, v39, v34
	v_exp_f32_e32 v43, v43
	v_sub_f32_e32 v44, v44, v115
	v_add_f32_e32 v34, v40, v34
	v_exp_f32_e32 v44, v44
	v_sub_f32_e32 v45, v45, v115
	v_add_f32_e32 v34, v41, v34
	v_exp_f32_e32 v45, v45
	v_sub_f32_e32 v46, v46, v115
	v_add_f32_e32 v34, v42, v34
	v_exp_f32_e32 v46, v46
	v_sub_f32_e32 v47, v47, v115
	v_add_f32_e32 v34, v43, v34
	v_exp_f32_e32 v47, v47
	v_sub_f32_e32 v48, v48, v115
	v_add_f32_e32 v34, v44, v34
	v_exp_f32_e32 v48, v48
	v_sub_f32_e32 v49, v49, v115
	v_add_f32_e32 v34, v45, v34
	v_exp_f32_e32 v49, v49
	v_add_f32_e32 v34, v46, v34
	v_add_f32_e32 v34, v47, v34
	s_mov_b32 s27, s56
	v_add_f32_e32 v34, v48, v34
	s_lshl_b64 s[10:11], s[26:27], 2
	v_add_f32_e32 v34, v49, v34
	s_add_u32 s10, s6, s10
	v_add_f32_e32 v50, v116, v34
	v_cvt_pk_bf16_f32 v34, v0, v35
	v_cvt_pk_bf16_f32 v35, v36, v37
	v_cvt_pk_bf16_f32 v36, v38, v39
	v_cvt_pk_bf16_f32 v37, v40, v41
	s_addc_u32 s11, s7, s11
	ds_bpermute_b32 v0, v112, v50
	s_waitcnt vmcnt(3)
	v_mfma_f32_32x32x16_bf16 v[2:17], v[58:61], v[34:37], v[2:17]
	v_cvt_pk_bf16_f32 v38, v42, v43
	v_cvt_pk_bf16_f32 v39, v44, v45
	v_cvt_pk_bf16_f32 v40, v46, v47
	s_waitcnt lgkmcnt(0)
	v_add_f32_e32 v0, v50, v0
	v_cvt_pk_bf16_f32 v41, v48, v49
	s_lshl_b32 s12, s9, 1
	s_mov_b32 s13, s56
	s_waitcnt vmcnt(1)
	v_mfma_f32_32x32x16_bf16 v[18:33], v[54:57], v[34:37], v[18:33]
	global_load_dword v34, v1, s[10:11]
	s_mov_b32 s10, 0x3fb8aa3b
	s_mov_b64 s[16:17], 0
	s_waitcnt vmcnt(0)
	v_fma_f32 v34, v34, s10, -v115
	v_exp_f32_e32 v34, v34
	v_mfma_f32_32x32x16_bf16 v[2:17], v[62:65], v[38:41], v[2:17]
	v_add_f32_e32 v0, v34, v0
	v_div_scale_f32 v34, s[10:11], v0, v0, 1.0
	v_rcp_f32_e32 v35, v34
	s_mov_b32 s10, 1
	v_mfma_f32_32x32x16_bf16 v[18:33], v[66:69], v[38:41], v[18:33]
	v_fma_f32 v36, -v34, v35, 1.0
	v_fmac_f32_e32 v35, v36, v35
	v_div_scale_f32 v36, vcc, 1.0, v0, 1.0
	v_mul_f32_e32 v37, v36, v35
	v_fma_f32 v38, -v34, v37, v36
	v_fmac_f32_e32 v37, v38, v35
	v_fma_f32 v34, -v34, v37, v36
	v_div_fmas_f32 v34, v34, v35, v37
	v_div_fixup_f32 v0, v34, v0, 1.0
	v_add_u32_e32 v34, s4, v114
	v_ashrrev_i32_e32 v35, 31, v34
	v_lshlrev_b64 v[34:35], 11, v[34:35]
	v_lshl_add_u64 v[34:35], s[0:1], 0, v[34:35]
	v_lshlrev_b32_e32 v36, 2, v113
	v_lshl_add_u64 v[34:35], v[34:35], 0, s[12:13]
	v_pk_mul_f32 v[2:3], v[2:3], v[0:1] op_sel_hi:[1,0]
	v_pk_mul_f32 v[4:5], v[4:5], v[0:1] op_sel_hi:[1,0]
	v_ashrrev_i32_e32 v37, 31, v36
	v_cvt_pk_bf16_f32 v2, v2, v3
	v_cvt_pk_bf16_f32 v3, v4, v5
	v_lshl_add_u64 v[34:35], v[36:37], 2, v[34:35]
	v_pk_mul_f32 v[6:7], v[6:7], v[0:1] op_sel_hi:[1,0]
	v_pk_mul_f32 v[8:9], v[8:9], v[0:1] op_sel_hi:[1,0]
	v_cvt_pk_bf16_f32 v4, v6, v7
	v_cvt_pk_bf16_f32 v5, v8, v9
	s_nop 1
	v_permlane32_swap_b32_e32 v2, v4
	v_permlane32_swap_b32_e32 v3, v5
	global_store_dwordx4 v[34:35], v[2:5], off
	v_pk_mul_f32 v[10:11], v[10:11], v[0:1] op_sel_hi:[1,0]
	v_pk_mul_f32 v[12:13], v[12:13], v[0:1] op_sel_hi:[1,0]
	v_cvt_pk_bf16_f32 v6, v10, v11
	v_cvt_pk_bf16_f32 v7, v12, v13
	v_pk_mul_f32 v[14:15], v[14:15], v[0:1] op_sel_hi:[1,0]
	v_pk_mul_f32 v[16:17], v[16:17], v[0:1] op_sel_hi:[1,0]
	v_cvt_pk_bf16_f32 v8, v14, v15
	v_cvt_pk_bf16_f32 v9, v16, v17
	s_nop 1
	v_permlane32_swap_b32_e32 v6, v8
	v_permlane32_swap_b32_e32 v7, v9
	global_store_dwordx4 v[34:35], v[6:9], off offset:32
	v_pk_mul_f32 v[18:19], v[18:19], v[0:1] op_sel_hi:[1,0]
	v_pk_mul_f32 v[20:21], v[20:21], v[0:1] op_sel_hi:[1,0]
	v_cvt_pk_bf16_f32 v10, v18, v19
	v_cvt_pk_bf16_f32 v11, v20, v21
	v_pk_mul_f32 v[22:23], v[22:23], v[0:1] op_sel_hi:[1,0]
	v_pk_mul_f32 v[24:25], v[24:25], v[0:1] op_sel_hi:[1,0]
	v_cvt_pk_bf16_f32 v12, v22, v23
	v_cvt_pk_bf16_f32 v13, v24, v25
	s_nop 1
	v_permlane32_swap_b32_e32 v10, v12
	v_permlane32_swap_b32_e32 v11, v13
	global_store_dwordx4 v[34:35], v[10:13], off offset:64
	v_pk_mul_f32 v[26:27], v[26:27], v[0:1] op_sel_hi:[1,0]
	v_pk_mul_f32 v[28:29], v[28:29], v[0:1] op_sel_hi:[1,0]
	v_cvt_pk_bf16_f32 v14, v26, v27
	v_cvt_pk_bf16_f32 v15, v28, v29
	v_pk_mul_f32 v[30:31], v[30:31], v[0:1] op_sel_hi:[1,0]
	v_pk_mul_f32 v[32:33], v[32:33], v[0:1] op_sel_hi:[1,0]
	v_cvt_pk_bf16_f32 v16, v30, v31
	v_cvt_pk_bf16_f32 v17, v32, v33
	s_and_b64 vcc, exec, s[24:25]
	s_nop 1
	v_permlane32_swap_b32_e32 v14, v16
	v_permlane32_swap_b32_e32 v15, v17
	global_store_dwordx4 v[34:35], v[14:17], off offset:96
	s_cbranch_vccnz .LBB0_657
